# FFN k-loop: 4 fragment sets (LDS read lookahead up to 3 MFMA groups)
# speedup vs baseline: 1.0075x; 1.0061x over previous
.LBB0_669:
	s_or_b64 exec, exec, s[18:19]
	v_add_co_u32_e32 v4, vcc, 0x7000, v30
	s_mul_i32 s18, s52, 62
	s_nop 0
	v_addc_co_u32_e32 v5, vcc, 0, v31, vcc
	global_load_dwordx4 v[110:113], v[4:5], off
	v_ashrrev_i32_e32 v4, 3, v41
	s_add_i32 s18, s3, s18
	v_lshrrev_b32_e32 v116, 4, v4
	s_add_i32 s18, s18, s51
	v_ashrrev_i32_e32 v8, 3, v40
	v_lshlrev_b64 v[4:5], 18, v[116:117]
	s_lshl_b32 s18, s18, 1
	v_lshl_add_u64 v[2:3], v[2:3], 1, v[4:5]
	v_lshrrev_b32_e32 v116, 4, v8
	v_subrev_u16_e32 v4, s18, v163
	v_ashrrev_i32_e32 v7, 3, v39
	v_lshl_add_u64 v[128:129], v[122:123], 0, v[2:3]
	v_lshlrev_b64 v[2:3], 18, v[116:117]
	v_and_b32_e32 v4, 0x7f, v4
	s_waitcnt lgkmcnt(0)
	s_barrier
	ds_read_b128 v[102:105], v168 offset:18432
	ds_read_b128 v[94:97], v168 offset:23040
	ds_read_b128 v[106:109], v169
	ds_read_b128 v[98:101], v169 offset:4608
	v_lshl_or_b32 v2, v4, 7, v2
	v_lshrrev_b32_e32 v116, 4, v7
	v_subrev_u16_e32 v4, s18, v164
	v_ashrrev_i32_e32 v6, 3, v38
	v_lshl_add_u64 v[130:131], v[122:123], 0, v[2:3]
	v_lshlrev_b64 v[2:3], 18, v[116:117]
	v_and_b32_e32 v4, 0x7f, v4
	v_lshl_or_b32 v2, v4, 7, v2
	v_lshrrev_b32_e32 v116, 4, v6
	v_subrev_u16_e32 v4, s18, v165
	v_lshl_add_u64 v[132:133], v[122:123], 0, v[2:3]
	v_lshlrev_b64 v[2:3], 18, v[116:117]
	v_and_b32_e32 v4, 0x7f, v4
	v_lshl_or_b32 v2, v4, 7, v2
	v_lshl_add_u64 v[134:135], v[122:123], 0, v[2:3]
	v_mov_b32_e32 v2, 0
	s_mov_b32 s15, 0
	v_lshl_add_u64 v[136:137], v[124:125], 0, s[16:17]
	s_mov_b64 s[16:17], 0
	v_mov_b32_e32 v3, v2
	v_mov_b32_e32 v4, v2
	v_mov_b32_e32 v5, v2
	v_mov_b32_e32 v6, v2
	v_mov_b32_e32 v7, v2
	v_mov_b32_e32 v8, v2
	v_mov_b32_e32 v9, v2
	v_mov_b32_e32 v10, v2
	v_mov_b32_e32 v11, v2
	v_mov_b32_e32 v12, v2
	v_mov_b32_e32 v13, v2
	v_mov_b32_e32 v14, v2
	v_mov_b32_e32 v15, v2
	v_mov_b32_e32 v16, v2
	v_mov_b32_e32 v17, v2
	v_mov_b32_e32 v18, v2
	v_mov_b32_e32 v19, v2
	v_mov_b32_e32 v20, v2
	v_mov_b32_e32 v21, v2
	v_mov_b32_e32 v22, v2
	v_mov_b32_e32 v23, v2
	v_mov_b32_e32 v24, v2
	v_mov_b32_e32 v25, v2
	v_mov_b32_e32 v26, v2
	v_mov_b32_e32 v27, v2
	v_mov_b32_e32 v28, v2
	v_mov_b32_e32 v29, v2
	v_mov_b32_e32 v30, v2
	v_mov_b32_e32 v31, v2
	v_mov_b32_e32 v32, v2
	v_mov_b32_e32 v33, v2
	v_mov_b32_e32 v34, v2
	v_mov_b32_e32 v35, v2
	v_mov_b32_e32 v36, v2
	v_mov_b32_e32 v37, v2
	v_mov_b32_e32 v38, v2
	v_mov_b32_e32 v39, v2
	v_mov_b32_e32 v40, v2
	v_mov_b32_e32 v41, v2
	v_mov_b32_e32 v42, v2
	v_mov_b32_e32 v43, v2
	v_mov_b32_e32 v44, v2
	v_mov_b32_e32 v45, v2
	v_mov_b32_e32 v46, v2
	v_mov_b32_e32 v47, v2
	v_mov_b32_e32 v48, v2
	v_mov_b32_e32 v49, v2
	v_mov_b32_e32 v50, v2
	v_mov_b32_e32 v51, v2
	v_mov_b32_e32 v52, v2
	v_mov_b32_e32 v53, v2
	v_mov_b32_e32 v54, v2
	v_mov_b32_e32 v55, v2
	v_mov_b32_e32 v56, v2
	v_mov_b32_e32 v57, v2
	v_mov_b32_e32 v58, v2
	v_mov_b32_e32 v59, v2
	v_mov_b32_e32 v60, v2
	v_mov_b32_e32 v61, v2
	v_mov_b32_e32 v62, v2
	v_mov_b32_e32 v63, v2
	v_mov_b32_e32 v64, v2
	v_mov_b32_e32 v65, v2
	s_mov_b32 s63, 0
	s_mov_b32 s62, 0x102c000
	v_lshl_add_u64 v[220:221], v[136:137], 0, s[62:63]
	s_mov_b32 s62, 0x102d000
	v_lshl_add_u64 v[222:223], v[136:137], 0, s[62:63]
	s_mov_b32 s62, 0x102e000
	v_lshl_add_u64 v[224:225], v[136:137], 0, s[62:63]
	s_mov_b32 s62, 0x102f000
	v_lshl_add_u64 v[226:227], v[136:137], 0, s[62:63]
	ds_read_b128 v[172:175], v168 offset:18464
	ds_read_b128 v[176:179], v168 offset:23072
	ds_read_b128 v[180:183], v169 offset:32
	ds_read_b128 v[184:187], v169 offset:4640
	ds_read_b128 v[188:191], v168 offset:18496
	ds_read_b128 v[192:195], v168 offset:23104
	ds_read_b128 v[196:199], v169 offset:64
	ds_read_b128 v[200:203], v169 offset:4672
	s_waitcnt lgkmcnt(8)
	ds_read_b128 v[204:207], v168 offset:18528
	ds_read_b128 v[208:211], v168 offset:23136
	ds_read_b128 v[212:215], v169 offset:96
	ds_read_b128 v[216:219], v169 offset:4704
	s_mov_b32 s64, 0
	s_mov_b32 s65, 0
	s_mov_b32 s66, 6
.Lk5_loop:
	s_waitcnt lgkmcnt(8)
	v_mfma_f32_32x32x16_bf16 v[50:65], v[102:105], v[106:109], v[50:65]
	s_waitcnt vmcnt(7)
	ds_write_b128 v140, v[66:69] offset:36864
	v_mfma_f32_32x32x16_bf16 v[34:49], v[94:97], v[106:109], v[34:49]
	s_waitcnt vmcnt(6)
	ds_write_b128 v140, v[74:77] offset:55296
	v_mfma_f32_32x32x16_bf16 v[18:33], v[102:105], v[98:101], v[18:33]
	s_waitcnt vmcnt(5)
	ds_write_b128 v142, v[70:73] offset:36864
	v_mfma_f32_32x32x16_bf16 v[2:17], v[94:97], v[98:101], v[2:17]
	s_waitcnt vmcnt(4)
	ds_write_b128 v142, v[82:85] offset:55296
	s_waitcnt lgkmcnt(8)
	v_mfma_f32_32x32x16_bf16 v[50:65], v[172:175], v[180:183], v[50:65]
	s_waitcnt vmcnt(3)
	ds_write_b128 v144, v[78:81] offset:36864
	v_mfma_f32_32x32x16_bf16 v[34:49], v[176:179], v[180:183], v[34:49]
	s_waitcnt vmcnt(2)
	ds_write_b128 v144, v[86:89] offset:55296
	v_mfma_f32_32x32x16_bf16 v[18:33], v[172:175], v[184:187], v[18:33]
	s_waitcnt vmcnt(1)
	ds_write_b128 v146, v[90:93] offset:36864
	v_mfma_f32_32x32x16_bf16 v[2:17], v[176:179], v[184:187], v[2:17]
	s_waitcnt vmcnt(0)
	ds_write_b128 v146, v[110:113] offset:55296
	s_waitcnt lgkmcnt(8)
	v_mfma_f32_32x32x16_bf16 v[50:65], v[188:191], v[196:199], v[50:65]
	s_mov_b64 exec, s[4:5]
	v_lshl_add_u64 v[66:67], v[134:135], 0, s[64:65]
	global_load_dwordx4 v[66:69], v[66:67], off
	s_mov_b64 exec, -1
	v_lshl_add_u64 v[74:75], v[220:221], 0, s[64:65]
	global_load_dwordx4 v[74:77], v[74:75], off
	v_mfma_f32_32x32x16_bf16 v[34:49], v[192:195], v[196:199], v[34:49]
	s_mov_b64 exec, s[6:7]
	v_lshl_add_u64 v[70:71], v[132:133], 0, s[64:65]
	global_load_dwordx4 v[70:73], v[70:71], off
	s_mov_b64 exec, -1
	v_lshl_add_u64 v[82:83], v[222:223], 0, s[64:65]
	global_load_dwordx4 v[82:85], v[82:83], off
	v_mfma_f32_32x32x16_bf16 v[18:33], v[188:191], v[200:203], v[18:33]
	s_mov_b64 exec, s[8:9]
	v_lshl_add_u64 v[78:79], v[130:131], 0, s[64:65]
	global_load_dwordx4 v[78:81], v[78:79], off
	s_mov_b64 exec, -1
	v_lshl_add_u64 v[86:87], v[224:225], 0, s[64:65]
	global_load_dwordx4 v[86:89], v[86:87], off
	v_mfma_f32_32x32x16_bf16 v[2:17], v[192:195], v[200:203], v[2:17]
	s_mov_b64 exec, s[10:11]
	v_lshl_add_u64 v[90:91], v[128:129], 0, s[64:65]
	global_load_dwordx4 v[90:93], v[90:91], off
	s_mov_b64 exec, -1
	v_lshl_add_u64 v[110:111], v[226:227], 0, s[64:65]
	global_load_dwordx4 v[110:113], v[110:111], off
	s_add_u32 s64, s64, 0x4000
	s_addc_u32 s65, s65, 0
	s_waitcnt lgkmcnt(0)
	s_barrier
	ds_read_b128 v[102:105], v168 offset:55296
	ds_read_b128 v[94:97], v168 offset:59904
	ds_read_b128 v[106:109], v169 offset:36864
	ds_read_b128 v[98:101], v169 offset:41472
	ds_read_b128 v[172:175], v168 offset:55328
	ds_read_b128 v[176:179], v168 offset:59936
	ds_read_b128 v[180:183], v169 offset:36896
	ds_read_b128 v[184:187], v169 offset:41504
	ds_read_b128 v[188:191], v168 offset:55360
	ds_read_b128 v[192:195], v168 offset:59968
	ds_read_b128 v[196:199], v169 offset:36928
	ds_read_b128 v[200:203], v169 offset:41536
	v_mfma_f32_32x32x16_bf16 v[50:65], v[204:207], v[212:215], v[50:65]
	v_mfma_f32_32x32x16_bf16 v[34:49], v[208:211], v[212:215], v[34:49]
	v_mfma_f32_32x32x16_bf16 v[18:33], v[204:207], v[216:219], v[18:33]
	v_mfma_f32_32x32x16_bf16 v[2:17], v[208:211], v[216:219], v[2:17]
	s_waitcnt lgkmcnt(8)
	ds_read_b128 v[204:207], v168 offset:55392
	ds_read_b128 v[208:211], v168 offset:60000
	ds_read_b128 v[212:215], v169 offset:36960
	ds_read_b128 v[216:219], v169 offset:41568
	s_waitcnt lgkmcnt(8)
	v_mfma_f32_32x32x16_bf16 v[50:65], v[102:105], v[106:109], v[50:65]
	s_waitcnt vmcnt(7)
	ds_write_b128 v140, v[66:69]
	v_mfma_f32_32x32x16_bf16 v[34:49], v[94:97], v[106:109], v[34:49]
	s_waitcnt vmcnt(6)
	ds_write_b128 v140, v[74:77] offset:18432
	v_mfma_f32_32x32x16_bf16 v[18:33], v[102:105], v[98:101], v[18:33]
	s_waitcnt vmcnt(5)
	ds_write_b128 v142, v[70:73]
	v_mfma_f32_32x32x16_bf16 v[2:17], v[94:97], v[98:101], v[2:17]
	s_waitcnt vmcnt(4)
	ds_write_b128 v142, v[82:85] offset:18432
	s_waitcnt lgkmcnt(8)
	v_mfma_f32_32x32x16_bf16 v[50:65], v[172:175], v[180:183], v[50:65]
	s_waitcnt vmcnt(3)
	ds_write_b128 v144, v[78:81]
	v_mfma_f32_32x32x16_bf16 v[34:49], v[176:179], v[180:183], v[34:49]
	s_waitcnt vmcnt(2)
	ds_write_b128 v144, v[86:89] offset:18432
	v_mfma_f32_32x32x16_bf16 v[18:33], v[172:175], v[184:187], v[18:33]
	s_waitcnt vmcnt(1)
	ds_write_b128 v146, v[90:93]
	v_mfma_f32_32x32x16_bf16 v[2:17], v[176:179], v[184:187], v[2:17]
	s_waitcnt vmcnt(0)
	ds_write_b128 v146, v[110:113] offset:18432
	s_waitcnt lgkmcnt(8)
	v_mfma_f32_32x32x16_bf16 v[50:65], v[188:191], v[196:199], v[50:65]
	s_mov_b64 exec, s[4:5]
	v_lshl_add_u64 v[66:67], v[134:135], 0, s[64:65]
	global_load_dwordx4 v[66:69], v[66:67], off
	s_mov_b64 exec, -1
	v_lshl_add_u64 v[74:75], v[220:221], 0, s[64:65]
	global_load_dwordx4 v[74:77], v[74:75], off
	v_mfma_f32_32x32x16_bf16 v[34:49], v[192:195], v[196:199], v[34:49]
	s_mov_b64 exec, s[6:7]
	v_lshl_add_u64 v[70:71], v[132:133], 0, s[64:65]
	global_load_dwordx4 v[70:73], v[70:71], off
	s_mov_b64 exec, -1
	v_lshl_add_u64 v[82:83], v[222:223], 0, s[64:65]
	global_load_dwordx4 v[82:85], v[82:83], off
	v_mfma_f32_32x32x16_bf16 v[18:33], v[188:191], v[200:203], v[18:33]
	s_mov_b64 exec, s[8:9]
	v_lshl_add_u64 v[78:79], v[130:131], 0, s[64:65]
	global_load_dwordx4 v[78:81], v[78:79], off
	s_mov_b64 exec, -1
	v_lshl_add_u64 v[86:87], v[224:225], 0, s[64:65]
	global_load_dwordx4 v[86:89], v[86:87], off
	v_mfma_f32_32x32x16_bf16 v[2:17], v[192:195], v[200:203], v[2:17]
	s_mov_b64 exec, s[10:11]
	v_lshl_add_u64 v[90:91], v[128:129], 0, s[64:65]
	global_load_dwordx4 v[90:93], v[90:91], off
	s_mov_b64 exec, -1
	v_lshl_add_u64 v[110:111], v[226:227], 0, s[64:65]
	global_load_dwordx4 v[110:113], v[110:111], off
	s_add_u32 s64, s64, 0x4000
	s_addc_u32 s65, s65, 0
	s_waitcnt lgkmcnt(0)
	s_barrier
	ds_read_b128 v[102:105], v168 offset:18432
	ds_read_b128 v[94:97], v168 offset:23040
	ds_read_b128 v[106:109], v169
	ds_read_b128 v[98:101], v169 offset:4608
	ds_read_b128 v[172:175], v168 offset:18464
	ds_read_b128 v[176:179], v168 offset:23072
	ds_read_b128 v[180:183], v169 offset:32
	ds_read_b128 v[184:187], v169 offset:4640
	ds_read_b128 v[188:191], v168 offset:18496
	ds_read_b128 v[192:195], v168 offset:23104
	ds_read_b128 v[196:199], v169 offset:64
	ds_read_b128 v[200:203], v169 offset:4672
	v_mfma_f32_32x32x16_bf16 v[50:65], v[204:207], v[212:215], v[50:65]
	v_mfma_f32_32x32x16_bf16 v[34:49], v[208:211], v[212:215], v[34:49]
	v_mfma_f32_32x32x16_bf16 v[18:33], v[204:207], v[216:219], v[18:33]
	v_mfma_f32_32x32x16_bf16 v[2:17], v[208:211], v[216:219], v[2:17]
	s_waitcnt lgkmcnt(8)
	ds_read_b128 v[204:207], v168 offset:18528
	ds_read_b128 v[208:211], v168 offset:23136
	ds_read_b128 v[212:215], v169 offset:96
	ds_read_b128 v[216:219], v169 offset:4704
	s_sub_u32 s66, s66, 1
	s_cmp_lg_u32 s66, 0
	s_cbranch_scc1 .Lk5_loop
	s_waitcnt lgkmcnt(8)
	v_mfma_f32_32x32x16_bf16 v[50:65], v[102:105], v[106:109], v[50:65]
	s_waitcnt vmcnt(7)
	ds_write_b128 v140, v[66:69] offset:36864
	v_mfma_f32_32x32x16_bf16 v[34:49], v[94:97], v[106:109], v[34:49]
	s_waitcnt vmcnt(6)
	ds_write_b128 v140, v[74:77] offset:55296
	v_mfma_f32_32x32x16_bf16 v[18:33], v[102:105], v[98:101], v[18:33]
	s_waitcnt vmcnt(5)
	ds_write_b128 v142, v[70:73] offset:36864
	v_mfma_f32_32x32x16_bf16 v[2:17], v[94:97], v[98:101], v[2:17]
	s_waitcnt vmcnt(4)
	ds_write_b128 v142, v[82:85] offset:55296
	s_waitcnt lgkmcnt(8)
	v_mfma_f32_32x32x16_bf16 v[50:65], v[172:175], v[180:183], v[50:65]
	s_waitcnt vmcnt(3)
	ds_write_b128 v144, v[78:81] offset:36864
	v_mfma_f32_32x32x16_bf16 v[34:49], v[176:179], v[180:183], v[34:49]
	s_waitcnt vmcnt(2)
	ds_write_b128 v144, v[86:89] offset:55296
	v_mfma_f32_32x32x16_bf16 v[18:33], v[172:175], v[184:187], v[18:33]
	s_waitcnt vmcnt(1)
	ds_write_b128 v146, v[90:93] offset:36864
	v_mfma_f32_32x32x16_bf16 v[2:17], v[176:179], v[184:187], v[2:17]
	s_waitcnt vmcnt(0)
	ds_write_b128 v146, v[110:113] offset:55296
	s_waitcnt lgkmcnt(8)
	v_mfma_f32_32x32x16_bf16 v[50:65], v[188:191], v[196:199], v[50:65]
	s_mov_b64 exec, s[4:5]
	v_lshl_add_u64 v[66:67], v[134:135], 0, s[64:65]
	global_load_dwordx4 v[66:69], v[66:67], off
	s_mov_b64 exec, -1
	v_lshl_add_u64 v[74:75], v[220:221], 0, s[64:65]
	global_load_dwordx4 v[74:77], v[74:75], off
	v_mfma_f32_32x32x16_bf16 v[34:49], v[192:195], v[196:199], v[34:49]
	s_mov_b64 exec, s[6:7]
	v_lshl_add_u64 v[70:71], v[132:133], 0, s[64:65]
	global_load_dwordx4 v[70:73], v[70:71], off
	s_mov_b64 exec, -1
	v_lshl_add_u64 v[82:83], v[222:223], 0, s[64:65]
	global_load_dwordx4 v[82:85], v[82:83], off
	v_mfma_f32_32x32x16_bf16 v[18:33], v[188:191], v[200:203], v[18:33]
	s_mov_b64 exec, s[8:9]
	v_lshl_add_u64 v[78:79], v[130:131], 0, s[64:65]
	global_load_dwordx4 v[78:81], v[78:79], off
	s_mov_b64 exec, -1
	v_lshl_add_u64 v[86:87], v[224:225], 0, s[64:65]
	global_load_dwordx4 v[86:89], v[86:87], off
	v_mfma_f32_32x32x16_bf16 v[2:17], v[192:195], v[200:203], v[2:17]
	s_mov_b64 exec, s[10:11]
	v_lshl_add_u64 v[90:91], v[128:129], 0, s[64:65]
	global_load_dwordx4 v[90:93], v[90:91], off
	s_mov_b64 exec, -1
	v_lshl_add_u64 v[110:111], v[226:227], 0, s[64:65]
	global_load_dwordx4 v[110:113], v[110:111], off
	s_add_u32 s64, s64, 0x4000
	s_addc_u32 s65, s65, 0
	s_waitcnt lgkmcnt(0)
	s_barrier
	ds_read_b128 v[102:105], v168 offset:55296
	ds_read_b128 v[94:97], v168 offset:59904
	ds_read_b128 v[106:109], v169 offset:36864
	ds_read_b128 v[98:101], v169 offset:41472
	ds_read_b128 v[172:175], v168 offset:55328
	ds_read_b128 v[176:179], v168 offset:59936
	ds_read_b128 v[180:183], v169 offset:36896
	ds_read_b128 v[184:187], v169 offset:41504
	ds_read_b128 v[188:191], v168 offset:55360
	ds_read_b128 v[192:195], v168 offset:59968
	ds_read_b128 v[196:199], v169 offset:36928
	ds_read_b128 v[200:203], v169 offset:41536
	v_mfma_f32_32x32x16_bf16 v[50:65], v[204:207], v[212:215], v[50:65]
	v_mfma_f32_32x32x16_bf16 v[34:49], v[208:211], v[212:215], v[34:49]
	v_mfma_f32_32x32x16_bf16 v[18:33], v[204:207], v[216:219], v[18:33]
	v_mfma_f32_32x32x16_bf16 v[2:17], v[208:211], v[216:219], v[2:17]
	s_waitcnt lgkmcnt(8)
	ds_read_b128 v[204:207], v168 offset:55392
	ds_read_b128 v[208:211], v168 offset:60000
	ds_read_b128 v[212:215], v169 offset:36960
	ds_read_b128 v[216:219], v169 offset:41568
	s_waitcnt lgkmcnt(8)
	v_mfma_f32_32x32x16_bf16 v[50:65], v[102:105], v[106:109], v[50:65]
	s_waitcnt vmcnt(7)
	ds_write_b128 v140, v[66:69]
	v_mfma_f32_32x32x16_bf16 v[34:49], v[94:97], v[106:109], v[34:49]
	s_waitcnt vmcnt(6)
	ds_write_b128 v140, v[74:77] offset:18432
	v_mfma_f32_32x32x16_bf16 v[18:33], v[102:105], v[98:101], v[18:33]
	s_waitcnt vmcnt(5)
	ds_write_b128 v142, v[70:73]
	v_mfma_f32_32x32x16_bf16 v[2:17], v[94:97], v[98:101], v[2:17]
	s_waitcnt vmcnt(4)
	ds_write_b128 v142, v[82:85] offset:18432
	s_waitcnt lgkmcnt(8)
	v_mfma_f32_32x32x16_bf16 v[50:65], v[172:175], v[180:183], v[50:65]
	s_waitcnt vmcnt(3)
	ds_write_b128 v144, v[78:81]
	v_mfma_f32_32x32x16_bf16 v[34:49], v[176:179], v[180:183], v[34:49]
	s_waitcnt vmcnt(2)
	ds_write_b128 v144, v[86:89] offset:18432
	v_mfma_f32_32x32x16_bf16 v[18:33], v[172:175], v[184:187], v[18:33]
	s_waitcnt vmcnt(1)
	ds_write_b128 v146, v[90:93]
	v_mfma_f32_32x32x16_bf16 v[2:17], v[176:179], v[184:187], v[2:17]
	s_waitcnt vmcnt(0)
	ds_write_b128 v146, v[110:113] offset:18432
	s_waitcnt lgkmcnt(8)
	v_mfma_f32_32x32x16_bf16 v[50:65], v[188:191], v[196:199], v[50:65]
	s_mov_b64 exec, s[4:5]
	v_lshl_add_u64 v[66:67], v[134:135], 0, s[64:65]
	global_load_dwordx4 v[66:69], v[66:67], off
	s_mov_b64 exec, -1
	v_lshl_add_u64 v[74:75], v[220:221], 0, s[64:65]
	global_load_dwordx4 v[74:77], v[74:75], off
	v_mfma_f32_32x32x16_bf16 v[34:49], v[192:195], v[196:199], v[34:49]
	s_mov_b64 exec, s[6:7]
	v_lshl_add_u64 v[70:71], v[132:133], 0, s[64:65]
	global_load_dwordx4 v[70:73], v[70:71], off
	s_mov_b64 exec, -1
	v_lshl_add_u64 v[82:83], v[222:223], 0, s[64:65]
	global_load_dwordx4 v[82:85], v[82:83], off
	v_mfma_f32_32x32x16_bf16 v[18:33], v[188:191], v[200:203], v[18:33]
	s_mov_b64 exec, s[8:9]
	v_lshl_add_u64 v[78:79], v[130:131], 0, s[64:65]
	global_load_dwordx4 v[78:81], v[78:79], off
	s_mov_b64 exec, -1
	v_lshl_add_u64 v[86:87], v[224:225], 0, s[64:65]
	global_load_dwordx4 v[86:89], v[86:87], off
	v_mfma_f32_32x32x16_bf16 v[2:17], v[192:195], v[200:203], v[2:17]
	s_mov_b64 exec, s[10:11]
	v_lshl_add_u64 v[90:91], v[128:129], 0, s[64:65]
	global_load_dwordx4 v[90:93], v[90:91], off
	s_mov_b64 exec, -1
	v_lshl_add_u64 v[110:111], v[226:227], 0, s[64:65]
	global_load_dwordx4 v[110:113], v[110:111], off
	s_add_u32 s64, s64, 0x4000
	s_addc_u32 s65, s65, 0
	s_waitcnt lgkmcnt(0)
	s_barrier
	ds_read_b128 v[102:105], v168 offset:18432
	ds_read_b128 v[94:97], v168 offset:23040
	ds_read_b128 v[106:109], v169
	ds_read_b128 v[98:101], v169 offset:4608
	v_mfma_f32_32x32x16_bf16 v[50:65], v[204:207], v[212:215], v[50:65]
	v_mfma_f32_32x32x16_bf16 v[34:49], v[208:211], v[212:215], v[34:49]
	v_mfma_f32_32x32x16_bf16 v[18:33], v[204:207], v[216:219], v[18:33]
	v_mfma_f32_32x32x16_bf16 v[2:17], v[208:211], v[216:219], v[2:17]
	s_branch .LBB0_679

.LBB0_2386:
	s_or_b64 exec, exec, s[22:23]
	v_add_co_u32_e32 v4, vcc, 0x7000, v30
	s_mul_i32 s22, s38, 62
	s_nop 0
	v_addc_co_u32_e32 v5, vcc, 0, v31, vcc
	global_load_dwordx4 v[110:113], v[4:5], off
	v_ashrrev_i32_e32 v4, 3, v41
	s_add_i32 s22, s24, s22
	v_lshrrev_b32_e32 v116, 4, v4
	s_add_i32 s22, s22, s37
	v_ashrrev_i32_e32 v8, 3, v40
	v_lshlrev_b64 v[4:5], 18, v[116:117]
	s_lshl_b32 s22, s22, 1
	v_lshl_add_u64 v[2:3], v[2:3], 1, v[4:5]
	v_lshrrev_b32_e32 v116, 4, v8
	v_subrev_u16_e32 v4, s22, v163
	v_ashrrev_i32_e32 v7, 3, v39
	v_lshl_add_u64 v[128:129], v[122:123], 0, v[2:3]
	v_lshlrev_b64 v[2:3], 18, v[116:117]
	v_and_b32_e32 v4, 0x7f, v4
	s_waitcnt lgkmcnt(0)
	s_barrier
	ds_read_b128 v[102:105], v168 offset:18432
	ds_read_b128 v[94:97], v168 offset:23040
	ds_read_b128 v[106:109], v169
	ds_read_b128 v[98:101], v169 offset:4608
	v_lshl_or_b32 v2, v4, 7, v2
	v_lshrrev_b32_e32 v116, 4, v7
	v_subrev_u16_e32 v4, s22, v164
	v_ashrrev_i32_e32 v6, 3, v38
	v_lshl_add_u64 v[130:131], v[122:123], 0, v[2:3]
	v_lshlrev_b64 v[2:3], 18, v[116:117]
	v_and_b32_e32 v4, 0x7f, v4
	v_lshl_or_b32 v2, v4, 7, v2
	v_lshrrev_b32_e32 v116, 4, v6
	v_subrev_u16_e32 v4, s22, v165
	v_lshl_add_u64 v[132:133], v[122:123], 0, v[2:3]
	v_lshlrev_b64 v[2:3], 18, v[116:117]
	v_and_b32_e32 v4, 0x7f, v4
	v_lshl_or_b32 v2, v4, 7, v2
	v_lshl_add_u64 v[134:135], v[122:123], 0, v[2:3]
	v_mov_b32_e32 v2, 0
	s_mov_b32 s19, 0
	v_lshl_add_u64 v[136:137], v[124:125], 0, s[20:21]
	s_mov_b64 s[20:21], 0
	v_mov_b32_e32 v3, v2
	v_mov_b32_e32 v4, v2
	v_mov_b32_e32 v5, v2
	v_mov_b32_e32 v6, v2
	v_mov_b32_e32 v7, v2
	v_mov_b32_e32 v8, v2
	v_mov_b32_e32 v9, v2
	v_mov_b32_e32 v10, v2
	v_mov_b32_e32 v11, v2
	v_mov_b32_e32 v12, v2
	v_mov_b32_e32 v13, v2
	v_mov_b32_e32 v14, v2
	v_mov_b32_e32 v15, v2
	v_mov_b32_e32 v16, v2
	v_mov_b32_e32 v17, v2
	v_mov_b32_e32 v18, v2
	v_mov_b32_e32 v19, v2
	v_mov_b32_e32 v20, v2
	v_mov_b32_e32 v21, v2
	v_mov_b32_e32 v22, v2
	v_mov_b32_e32 v23, v2
	v_mov_b32_e32 v24, v2
	v_mov_b32_e32 v25, v2
	v_mov_b32_e32 v26, v2
	v_mov_b32_e32 v27, v2
	v_mov_b32_e32 v28, v2
	v_mov_b32_e32 v29, v2
	v_mov_b32_e32 v30, v2
	v_mov_b32_e32 v31, v2
	v_mov_b32_e32 v32, v2
	v_mov_b32_e32 v33, v2
	v_mov_b32_e32 v34, v2
	v_mov_b32_e32 v35, v2
	v_mov_b32_e32 v36, v2
	v_mov_b32_e32 v37, v2
	v_mov_b32_e32 v38, v2
	v_mov_b32_e32 v39, v2
	v_mov_b32_e32 v40, v2
	v_mov_b32_e32 v41, v2
	v_mov_b32_e32 v42, v2
	v_mov_b32_e32 v43, v2
	v_mov_b32_e32 v44, v2
	v_mov_b32_e32 v45, v2
	v_mov_b32_e32 v46, v2
	v_mov_b32_e32 v47, v2
	v_mov_b32_e32 v48, v2
	v_mov_b32_e32 v49, v2
	v_mov_b32_e32 v50, v2
	v_mov_b32_e32 v51, v2
	v_mov_b32_e32 v52, v2
	v_mov_b32_e32 v53, v2
	v_mov_b32_e32 v54, v2
	v_mov_b32_e32 v55, v2
	v_mov_b32_e32 v56, v2
	v_mov_b32_e32 v57, v2
	v_mov_b32_e32 v58, v2
	v_mov_b32_e32 v59, v2
	v_mov_b32_e32 v60, v2
	v_mov_b32_e32 v61, v2
	v_mov_b32_e32 v62, v2
	v_mov_b32_e32 v63, v2
	v_mov_b32_e32 v64, v2
	v_mov_b32_e32 v65, v2
	s_mov_b32 s63, 0
	s_mov_b32 s62, 0x1b2c000
	v_lshl_add_u64 v[220:221], v[136:137], 0, s[62:63]
	s_mov_b32 s62, 0x1b2d000
	v_lshl_add_u64 v[222:223], v[136:137], 0, s[62:63]
	s_mov_b32 s62, 0x1b2e000
	v_lshl_add_u64 v[224:225], v[136:137], 0, s[62:63]
	s_mov_b32 s62, 0x1b2f000
	v_lshl_add_u64 v[226:227], v[136:137], 0, s[62:63]
	ds_read_b128 v[172:175], v168 offset:18464
	ds_read_b128 v[176:179], v168 offset:23072
	ds_read_b128 v[180:183], v169 offset:32
	ds_read_b128 v[184:187], v169 offset:4640
	ds_read_b128 v[188:191], v168 offset:18496
	ds_read_b128 v[192:195], v168 offset:23104
	ds_read_b128 v[196:199], v169 offset:64
	ds_read_b128 v[200:203], v169 offset:4672
	s_waitcnt lgkmcnt(8)
	ds_read_b128 v[204:207], v168 offset:18528
	ds_read_b128 v[208:211], v168 offset:23136
	ds_read_b128 v[212:215], v169 offset:96
	ds_read_b128 v[216:219], v169 offset:4704
	s_mov_b32 s64, 0
	s_mov_b32 s65, 0
	s_mov_b32 s66, 6
